# speedup vs baseline: 1.0176x; 1.0040x over previous
.LBB0_49:
	v_mov_b32_e32 v218, v184
	s_and_b64 s[0:1], s[38:39], exec
	s_cselect_b32 s8, s94, s97
	v_readfirstlane_b32 s12, v218
	s_ashr_i32 s9, s12, 6
	s_lshl_b32 s0, s9, 3
	s_waitcnt vmcnt(0)
	v_bfe_u32 v181, v218, 4, 2
	v_bitop3_b32 v1, s0, v218, v181 bitop3:0x36
	v_lshlrev_b32_e32 v1, 4, v1
	v_or_b32_e32 v0, s0, v181
	v_and_b32_e32 v182, 0xf0, v1
	v_lshl_or_b32 v4, v0, 13, v182
	v_or_b32_e32 v1, 4, v0
	v_bitop3_b32 v0, v0, v218, 4 bitop3:0x36
	v_lshlrev_b32_e32 v0, 4, v0
	s_lshl_b32 s95, s9, 11
	v_and_b32_e32 v183, 0xf0, v0
	s_or_b32 s0, s95, 0x400
	s_mov_b32 m0, s95
	v_lshl_or_b32 v6, v1, 13, v183
	global_load_lds_dwordx4 v4, s[76:77]
	s_mov_b32 m0, s0
	s_and_b32 s13, s9, 3
	global_load_lds_dwordx4 v6, s[76:77]
	s_add_i32 s0, s8, 0x80
	s_lshl_b32 s2, s13, 5
	s_lshr_b32 s33, s0, 6
	s_lshr_b32 s0, s12, 1
	v_and_b32_e32 v180, 31, v218
	s_or_b32 s3, s2, s8
	v_bfe_u32 v219, v218, 5, 1
	v_lshlrev_b32_e32 v0, 3, v218
	s_and_b32 s10, s0, 0x7fffff80
	s_lshl_b32 s11, s13, 16
	v_mov_b32_e32 v5, v2
	v_mov_b32_e32 v7, v2
	v_and_b32_e32 v216, 63, v218
	v_and_b32_e32 v213, 24, v0
	v_bfe_u32 v215, v180, 2, 2
	v_and_b32_e32 v214, 32, v218
	s_cmp_gt_i32 s9, 3
	v_lshlrev_b32_e32 v217, 2, v219
	v_lshl_add_u64 v[166:167], s[80:81], 0, v[4:5]
	v_lshl_add_u64 v[0:1], s[80:81], 0, v[6:7]
	s_mov_b64 s[6:7], -1
	s_cbranch_scc0 .LBB0_321
	s_add_i32 m0, s95, 0x4000
	s_nop 0
	global_load_lds_dwordx4 v[166:167], off
	s_add_i32 m0, s95, 0x4400
	s_cmp_eq_u32 s8, 0
	global_load_lds_dwordx4 v[0:1], off
	s_waitcnt vmcnt(0) lgkmcnt(0)
	s_waitcnt vmcnt(0) lgkmcnt(0)
	s_barrier
	s_waitcnt vmcnt(0) lgkmcnt(0)
	s_barrier
	s_cbranch_scc1 .LBB0_52
	s_mov_b32 m0, s95
	v_lshl_add_u64 v[4:5], s[82:83], 0, v[4:5]
	v_lshl_add_u64 v[6:7], s[82:83], 0, v[6:7]
	global_load_lds_dwordx4 v[4:5], off
	s_add_i32 m0, s95, 0x400
	s_nop 0
	global_load_lds_dwordx4 v[6:7], off
	s_mov_b32 s98, 0xfffc0000
	s_mov_b32 s99, -1
	v_lshl_add_u64 v[226:227], v[4:5], 0, s[98:99]
	s_add_i32 m0, s95, 0xffffe000
	v_lshl_add_u64 v[228:229], v[6:7], 0, s[98:99]
	global_load_lds_dwordx4 v[226:227], off
	s_add_i32 m0, s95, 0xffffe400
	s_nop 0
	global_load_lds_dwordx4 v[228:229], off
.LBB0_52:
	v_bfe_u32 v3, v218, 2, 3
	v_lshlrev_b32_e32 v3, 1, v3
	v_and_or_b32 v3, v3, 8, v215
	s_lshl_b32 s0, s9, 12
	v_lshl_or_b32 v3, v3, 12, s11
	s_and_b32 s0, s0, 0x7fffc000
	s_lshl_b32 s5, s13, 12
	v_or_b32_e32 v7, v213, v214
	v_add_u32_e32 v3, s10, v3
	s_or_b32 s0, s5, s0
	v_or_b32_e32 v8, v3, v7
	v_or_b32_e32 v9, 64, v7
	v_lshlrev_b32_e32 v8, 1, v8
	v_or_b32_e32 v10, v3, v9
	v_add_u32_e32 v3, 0x4000, v3
	s_add_i32 m0, s0, 0x8000
	v_lshlrev_b32_e32 v10, 1, v10
	v_or_b32_e32 v7, v3, v7
	global_load_lds_dwordx4 v8, s[78:79]
	s_add_i32 m0, s0, 0x8400
	v_lshlrev_b32_e32 v7, 1, v7
	v_or_b32_e32 v3, v3, v9
	global_load_lds_dwordx4 v10, s[78:79]
	s_add_i32 m0, s0, 0x8800
	v_lshlrev_b32_e32 v3, 1, v3
	global_load_lds_dwordx4 v7, s[78:79]
	s_add_i32 m0, s0, 0x8c00
	v_lshlrev_b32_e32 v4, 4, v216
	global_load_lds_dwordx4 v3, s[78:79]
	v_add_u32_e32 v222, 0xffffff00, v8
	s_add_i32 m0, s0, 0x4000
	v_add_u32_e32 v223, 0xffffff00, v10
	global_load_lds_dwordx4 v222, s[78:79]
	s_add_i32 m0, s0, 0x4400
	v_add_u32_e32 v224, 0xffffff00, v7
	global_load_lds_dwordx4 v223, s[78:79]
	s_add_i32 m0, s0, 0x4800
	v_add_u32_e32 v225, 0xffffff00, v3
	global_load_lds_dwordx4 v224, s[78:79]
	s_add_i32 m0, s0, 0x4c00
	s_nop 0
	global_load_lds_dwordx4 v225, s[78:79]
	v_lshlrev_b32_e32 v6, 3, v216
	v_lshlrev_b32_e32 v5, 1, v216
	v_and_b32_e32 v3, 0xc0, v4
	v_and_b32_e32 v6, 0x118, v6
	v_or_b32_e32 v4, s5, v4
	v_or_b32_e32 v221, 0x18000, v4
	s_mov_b32 s14, 0x8000
	v_and_or_b32 v4, v5, 32, v6
	v_or3_b32 v220, v3, v4, s14
	v_lshlrev_b32_e32 v3, 11, v180
	s_lshl_b32 s6, s8, 13
	v_and_b32_e32 v3, 0x8000, v3
	v_lshlrev_b32_e32 v6, 12, v215
	s_add_i32 s6, s6, 0x100000
	v_add3_u32 v4, s11, v3, v6
	s_and_b32 s6, s6, 0x7f80000
	v_add3_u32 v4, v4, s10, v214
	s_add_u32 s15, s6, 0xfff80000
	v_add_lshl_u32 v4, v4, v213, 1
	v_mov_b32_e32 v5, v2
	s_add_i32 s6, s11, 64
	v_lshl_add_u64 v[168:169], s[84:85], 0, v[4:5]
	v_add3_u32 v4, s6, v3, v6
	v_add3_u32 v4, v4, s10, v214
	v_add_lshl_u32 v4, v4, v213, 1
	s_add_i32 s6, s11, 0x4000
	v_lshl_add_u64 v[170:171], s[84:85], 0, v[4:5]
	v_add3_u32 v4, s6, v3, v6
	s_add_i32 s6, s11, 0x4040
	v_add3_u32 v4, v4, s10, v214
	v_add3_u32 v3, s6, v3, v6
	v_add_lshl_u32 v4, v4, v213, 1
	v_add3_u32 v3, v3, s10, v214
	s_lshl_b32 s6, s9, 16
	v_lshl_add_u64 v[172:173], s[84:85], 0, v[4:5]
	v_add_lshl_u32 v4, v3, v213, 1
	v_lshl_or_b32 v3, v181, 13, s6
	v_lshl_add_u64 v[174:175], s[84:85], 0, v[4:5]
	v_or_b32_e32 v4, v3, v182
	s_waitcnt vmcnt(0) lgkmcnt(0)
	v_lshl_add_u64 v[176:177], s[86:87], 0, v[4:5]
	v_or3_b32 v4, v3, v183, s14
	v_mov_b32_e32 v16, v2
	v_mov_b32_e32 v17, v2
	s_lshl_b32 s1, s2, 2
	v_lshl_add_u64 v[178:179], s[86:87], 0, v[4:5]
	v_mov_b32_e32 v3, v2
	v_mov_b32_e32 v4, v2
	v_mov_b32_e32 v6, v2
	v_mov_b32_e32 v7, v2
	v_mov_b32_e32 v8, v2
	v_mov_b32_e32 v9, v2
	v_mov_b32_e32 v10, v2
	v_mov_b32_e32 v11, v2
	v_mov_b32_e32 v12, v2
	v_mov_b32_e32 v13, v2
	v_mov_b32_e32 v14, v2
	v_mov_b32_e32 v15, v2
	v_mov_b64_e32 v[32:33], v[16:17]
	v_mov_b64_e32 v[48:49], v[16:17]
	v_mov_b64_e32 v[64:65], v[16:17]
	v_mov_b64_e32 v[80:81], v[16:17]
	v_mov_b64_e32 v[96:97], v[16:17]
	v_mov_b64_e32 v[112:113], v[16:17]
	v_mov_b64_e32 v[128:129], v[16:17]
	v_mov_b64_e32 v[144:145], v[16:17]
	s_bitset1_b32 s1, 17
	s_or_b32 s4, s3, 31
	s_movk_i32 s5, 0x4000
	s_mov_b64 s[6:7], 0
	s_mov_b32 s16, 0
	s_mov_b32 s17, 0
	v_mov_b64_e32 v[30:31], v[14:15]
	v_mov_b64_e32 v[28:29], v[12:13]
	v_mov_b64_e32 v[26:27], v[10:11]
	v_mov_b64_e32 v[24:25], v[8:9]
	v_mov_b64_e32 v[22:23], v[6:7]
	v_mov_b64_e32 v[20:21], v[4:5]
	v_mov_b64_e32 v[18:19], v[2:3]
	v_mov_b64_e32 v[46:47], v[14:15]
	v_mov_b64_e32 v[44:45], v[12:13]
	v_mov_b64_e32 v[42:43], v[10:11]
	v_mov_b64_e32 v[40:41], v[8:9]
	v_mov_b64_e32 v[38:39], v[6:7]
	v_mov_b64_e32 v[36:37], v[4:5]
	v_mov_b64_e32 v[34:35], v[2:3]
	v_mov_b64_e32 v[62:63], v[14:15]
	v_mov_b64_e32 v[60:61], v[12:13]
	v_mov_b64_e32 v[58:59], v[10:11]
	v_mov_b64_e32 v[56:57], v[8:9]
	v_mov_b64_e32 v[54:55], v[6:7]
	v_mov_b64_e32 v[52:53], v[4:5]
	v_mov_b64_e32 v[50:51], v[2:3]
	v_mov_b64_e32 v[78:79], v[14:15]
	v_mov_b64_e32 v[76:77], v[12:13]
	v_mov_b64_e32 v[74:75], v[10:11]
	v_mov_b64_e32 v[72:73], v[8:9]
	v_mov_b64_e32 v[70:71], v[6:7]
	v_mov_b64_e32 v[68:69], v[4:5]
	v_mov_b64_e32 v[66:67], v[2:3]
	v_mov_b64_e32 v[94:95], v[14:15]
	v_mov_b64_e32 v[92:93], v[12:13]
	v_mov_b64_e32 v[90:91], v[10:11]
	v_mov_b64_e32 v[88:89], v[8:9]
	v_mov_b64_e32 v[86:87], v[6:7]
	v_mov_b64_e32 v[84:85], v[4:5]
	v_mov_b64_e32 v[82:83], v[2:3]
	v_mov_b64_e32 v[110:111], v[14:15]
	v_mov_b64_e32 v[108:109], v[12:13]
	v_mov_b64_e32 v[106:107], v[10:11]
	v_mov_b64_e32 v[104:105], v[8:9]
	v_mov_b64_e32 v[102:103], v[6:7]
	v_mov_b64_e32 v[100:101], v[4:5]
	v_mov_b64_e32 v[98:99], v[2:3]
	v_mov_b64_e32 v[126:127], v[14:15]
	v_mov_b64_e32 v[124:125], v[12:13]
	v_mov_b64_e32 v[122:123], v[10:11]
	v_mov_b64_e32 v[120:121], v[8:9]
	v_mov_b64_e32 v[118:119], v[6:7]
	v_mov_b64_e32 v[116:117], v[4:5]
	v_mov_b64_e32 v[114:115], v[2:3]
	v_mov_b64_e32 v[142:143], v[14:15]
	v_mov_b64_e32 v[140:141], v[12:13]
	v_mov_b64_e32 v[138:139], v[10:11]
	v_mov_b64_e32 v[136:137], v[8:9]
	v_mov_b64_e32 v[134:135], v[6:7]
	v_mov_b64_e32 v[132:133], v[4:5]
	v_mov_b64_e32 v[130:131], v[2:3]
	s_waitcnt vmcnt(0) lgkmcnt(0)
	s_barrier
	s_branch .LBB0_55

.LBB0_55:
	s_add_i32 s18, s17, 3
	s_cmp_ge_u32 s18, s33
	s_cbranch_scc1 .LBB0_57
	s_and_b32 s18, s5, 0x4000
	s_add_i32 s18, s95, s18
	s_sub_u32 s98, s6, 0x40000
	s_subb_u32 s99, s7, 0
	v_lshl_add_u64 v[226:227], v[176:177], 0, s[98:99]
	s_add_i32 m0, s18, 0xffffe000
	v_lshl_add_u64 v[228:229], v[178:179], 0, s[98:99]
	global_load_lds_dwordx4 v[226:227], off
	s_add_i32 m0, s18, 0xffffe400
	s_nop 0
	global_load_lds_dwordx4 v[228:229], off
	v_lshl_add_u64 v[4:5], v[176:177], 0, s[6:7]
	s_add_i32 s19, s18, 0x400
	s_mov_b32 m0, s18
	v_lshl_add_u64 v[6:7], v[178:179], 0, s[6:7]
	global_load_lds_dwordx4 v[4:5], off
	s_mov_b32 m0, s19
	s_nop 0
	global_load_lds_dwordx4 v[6:7], off
.LBB0_57:
	s_and_b32 s18, s14, 0x8000
	s_add_i32 s18, s0, s18
	s_add_u32 s98, s6, 0xffffff00
	s_addc_u32 s99, s7, -1
	v_lshl_add_u64 v[222:223], v[168:169], 0, s[98:99]
	s_add_i32 m0, s18, 0x4000
	v_lshl_add_u64 v[224:225], v[170:171], 0, s[98:99]
	global_load_lds_dwordx4 v[222:223], off
	s_add_i32 m0, s18, 0x4400
	v_lshl_add_u64 v[222:223], v[172:173], 0, s[98:99]
	global_load_lds_dwordx4 v[224:225], off
	s_add_i32 m0, s18, 0x4800
	v_lshl_add_u64 v[224:225], v[174:175], 0, s[98:99]
	global_load_lds_dwordx4 v[222:223], off
	s_add_i32 m0, s18, 0x4c00
	s_nop 0
	global_load_lds_dwordx4 v[224:225], off
	s_add_i32 m0, s18, 0x8000
	v_lshl_add_u64 v[4:5], v[168:169], 0, s[6:7]
	global_load_lds_dwordx4 v[4:5], off
	v_lshl_add_u64 v[4:5], v[170:171], 0, s[6:7]
	s_add_i32 m0, s18, 0x8400
	s_nop 0
	global_load_lds_dwordx4 v[4:5], off
	v_lshl_add_u64 v[4:5], v[172:173], 0, s[6:7]
	s_add_i32 m0, s18, 0x8800
	s_nop 0
	global_load_lds_dwordx4 v[4:5], off
	v_lshl_add_u64 v[4:5], v[174:175], 0, s[6:7]
	s_add_i32 m0, s18, 0x8c00
	s_cmp_gt_u32 s16, s4
	global_load_lds_dwordx4 v[4:5], off
	s_cbranch_scc1 .LBB0_54
	s_and_b32 s18, s17, 1
	s_lshl_b32 s19, s18, 9
	s_add_i32 s19, s1, s19
	v_lshl_add_u32 v4, v180, 2, s19
	v_lshl_add_u32 v3, s18, 14, v221
	ds_read_b32 v16, v4
	ds_read_b128 v[146:149], v3
	ds_read_b128 v[12:15], v3 offset:1024
	ds_read_b128 v[8:11], v3 offset:2048
	ds_read_b128 v[4:7], v3 offset:3072
	s_waitcnt lgkmcnt(0)
	v_cmp_gt_f32_e32 vcc, 1.0, v16
	s_cbranch_vccz .LBB0_53
	v_lshl_add_u32 v3, v217, 2, s19
	ds_read_b128 v[162:165], v3 offset:96
	ds_read_b128 v[158:161], v3 offset:64
	ds_read_b128 v[154:157], v3 offset:32
	ds_read_b128 v[150:153], v3
	s_waitcnt lgkmcnt(0)
	v_pk_mul_f32 v[144:145], v[144:145], v[164:165]
	v_pk_mul_f32 v[140:141], v[140:141], v[160:161]
	v_pk_mul_f32 v[136:137], v[136:137], v[156:157]
	v_pk_mul_f32 v[132:133], v[132:133], v[152:153]
	v_pk_mul_f32 v[142:143], v[142:143], v[162:163]
	v_pk_mul_f32 v[138:139], v[138:139], v[158:159]
	v_pk_mul_f32 v[134:135], v[134:135], v[154:155]
	v_pk_mul_f32 v[130:131], v[130:131], v[150:151]
	v_pk_mul_f32 v[128:129], v[128:129], v[164:165]
	v_pk_mul_f32 v[124:125], v[124:125], v[160:161]
	v_pk_mul_f32 v[120:121], v[120:121], v[156:157]
	v_pk_mul_f32 v[116:117], v[116:117], v[152:153]
	v_pk_mul_f32 v[126:127], v[126:127], v[162:163]
	v_pk_mul_f32 v[122:123], v[122:123], v[158:159]
	v_pk_mul_f32 v[118:119], v[118:119], v[154:155]
	v_pk_mul_f32 v[114:115], v[114:115], v[150:151]
	v_pk_mul_f32 v[112:113], v[112:113], v[164:165]
	v_pk_mul_f32 v[108:109], v[108:109], v[160:161]
	v_pk_mul_f32 v[104:105], v[104:105], v[156:157]
	v_pk_mul_f32 v[100:101], v[100:101], v[152:153]
	v_pk_mul_f32 v[110:111], v[110:111], v[162:163]
	v_pk_mul_f32 v[106:107], v[106:107], v[158:159]
	v_pk_mul_f32 v[102:103], v[102:103], v[154:155]
	v_pk_mul_f32 v[98:99], v[98:99], v[150:151]
	v_pk_mul_f32 v[96:97], v[96:97], v[164:165]
	v_pk_mul_f32 v[92:93], v[92:93], v[160:161]
	v_pk_mul_f32 v[88:89], v[88:89], v[156:157]
	v_pk_mul_f32 v[84:85], v[84:85], v[152:153]
	v_pk_mul_f32 v[94:95], v[94:95], v[162:163]
	v_pk_mul_f32 v[90:91], v[90:91], v[158:159]
	v_pk_mul_f32 v[86:87], v[86:87], v[154:155]
	v_pk_mul_f32 v[82:83], v[82:83], v[150:151]
	v_pk_mul_f32 v[80:81], v[80:81], v[164:165]
	v_pk_mul_f32 v[76:77], v[76:77], v[160:161]
	v_pk_mul_f32 v[72:73], v[72:73], v[156:157]
	v_pk_mul_f32 v[68:69], v[68:69], v[152:153]
	v_pk_mul_f32 v[78:79], v[78:79], v[162:163]
	v_pk_mul_f32 v[74:75], v[74:75], v[158:159]
	v_pk_mul_f32 v[70:71], v[70:71], v[154:155]
	v_pk_mul_f32 v[66:67], v[66:67], v[150:151]
	v_pk_mul_f32 v[64:65], v[64:65], v[164:165]
	v_pk_mul_f32 v[60:61], v[60:61], v[160:161]
	v_pk_mul_f32 v[56:57], v[56:57], v[156:157]
	v_pk_mul_f32 v[52:53], v[52:53], v[152:153]
	v_pk_mul_f32 v[62:63], v[62:63], v[162:163]
	v_pk_mul_f32 v[58:59], v[58:59], v[158:159]
	v_pk_mul_f32 v[54:55], v[54:55], v[154:155]
	v_pk_mul_f32 v[50:51], v[50:51], v[150:151]
	v_pk_mul_f32 v[48:49], v[48:49], v[164:165]
	v_pk_mul_f32 v[44:45], v[44:45], v[160:161]
	v_pk_mul_f32 v[40:41], v[40:41], v[156:157]
	v_pk_mul_f32 v[36:37], v[36:37], v[152:153]
	v_pk_mul_f32 v[46:47], v[46:47], v[162:163]
	v_pk_mul_f32 v[42:43], v[42:43], v[158:159]
	v_pk_mul_f32 v[38:39], v[38:39], v[154:155]
	v_pk_mul_f32 v[34:35], v[34:35], v[150:151]
	v_pk_mul_f32 v[32:33], v[32:33], v[164:165]
	v_pk_mul_f32 v[28:29], v[28:29], v[160:161]
	v_pk_mul_f32 v[24:25], v[24:25], v[156:157]
	v_pk_mul_f32 v[20:21], v[20:21], v[152:153]
	v_pk_mul_f32 v[30:31], v[30:31], v[162:163]
	v_pk_mul_f32 v[26:27], v[26:27], v[158:159]
	v_pk_mul_f32 v[22:23], v[22:23], v[154:155]
	v_pk_mul_f32 v[18:19], v[18:19], v[150:151]
	s_branch .LBB0_53

.LBB0_325:
	s_add_i32 s8, s74, 2
	s_cmp_ge_u32 s8, s33
	s_cbranch_scc1 .LBB0_327
	s_add_i32 s8, s4, 0xffffc000
	s_and_b32 s8, s8, 0x4000
	s_add_i32 s8, s95, s8
	v_lshl_add_u64 v[4:5], v[136:137], 0, s[92:93]
	s_add_i32 s9, s8, 0x400
	s_mov_b32 m0, s8
	v_lshl_add_u64 v[6:7], v[138:139], 0, s[92:93]
	s_mov_b32 m0, s9
	s_nop 0
.LBB0_327:
	s_cmp_ge_u32 s74, s33
	s_cbranch_scc1 .LBB0_324
	s_and_b32 s8, s5, 0x8000
	s_add_i32 s8, s72, s8
	s_add_i32 m0, s8, 0x8000
	v_lshl_add_u64 v[4:5], v[0:1], 0, s[92:93]
	v_lshl_add_u64 v[4:5], v[130:131], 0, s[92:93]
	s_add_i32 m0, s8, 0x8400
	s_nop 0
	v_lshl_add_u64 v[4:5], v[132:133], 0, s[92:93]
	s_add_i32 m0, s8, 0x8800
	s_nop 0
	v_lshl_add_u64 v[4:5], v[134:135], 0, s[92:93]
	s_add_i32 m0, s8, 0x8c00
	s_sub_i32 s8, s73, 63
	s_cmp_gt_u32 s8, s1
	s_cbranch_scc1 .LBB0_324
	s_cmp_le_u32 s73, s3
	s_cbranch_scc1 .LBB0_331
	v_cmp_gt_i32_e64 s[68:69], 26, v151
	v_cmp_gt_i32_e64 s[70:71], 27, v151
	v_cmp_gt_i32_e64 s[66:67], 25, v151
	s_and_b64 s[68:69], s[70:71], s[68:69]
	v_cmp_gt_i32_e64 s[64:65], 24, v151
	s_and_b64 s[66:67], s[68:69], s[66:67]
	v_cmp_gt_i32_e64 s[62:63], 19, v151
	s_and_b64 s[64:65], s[66:67], s[64:65]
	v_cmp_gt_i32_e64 s[60:61], 18, v151
	s_and_b64 s[62:63], s[64:65], s[62:63]
	v_cmp_gt_i32_e64 s[58:59], 17, v151
	s_and_b64 s[60:61], s[62:63], s[60:61]
	v_cmp_gt_i32_e64 s[56:57], 16, v151
	s_and_b64 s[58:59], s[60:61], s[58:59]
	v_cmp_gt_i32_e64 s[54:55], 11, v151
	s_and_b64 s[56:57], s[58:59], s[56:57]
	v_cmp_gt_i32_e64 s[52:53], 10, v151
	s_and_b64 s[54:55], s[56:57], s[54:55]
	v_cmp_gt_i32_e64 s[50:51], 9, v151
	s_and_b64 s[52:53], s[54:55], s[52:53]
	v_cmp_gt_i32_e64 s[48:49], 8, v151
	s_and_b64 s[50:51], s[52:53], s[50:51]
	v_cmp_gt_i32_e64 s[46:47], 3, v151
	s_and_b64 s[48:49], s[50:51], s[48:49]
	v_cmp_gt_i32_e64 s[44:45], 2, v151
	s_and_b64 s[46:47], s[48:49], s[46:47]
	v_cmp_gt_i32_e64 s[42:43], 1, v151
	s_and_b64 s[44:45], s[46:47], s[44:45]
	v_cmp_gt_i32_e64 s[40:41], 0, v151
	s_and_b64 s[42:43], s[44:45], s[42:43]
	s_and_b64 s[40:41], s[42:43], s[40:41]
	v_cmp_gt_i32_e64 s[36:37], 58, v151
	v_cndmask_b32_e64 v50, v34, v210, s[40:41]
	v_cmp_gt_i32_e64 s[40:41], 59, v151
	v_cmp_gt_i32_e64 s[34:35], 57, v151
	s_and_b64 s[36:37], s[40:41], s[36:37]
	v_cmp_gt_i32_e64 s[30:31], 56, v151
	s_and_b64 s[34:35], s[36:37], s[34:35]
	v_cmp_gt_i32_e64 s[28:29], 51, v151
	s_and_b64 s[30:31], s[34:35], s[30:31]
	v_cmp_gt_i32_e64 s[26:27], 50, v151
	s_and_b64 s[28:29], s[30:31], s[28:29]
	v_cmp_gt_i32_e64 s[24:25], 49, v151
	s_and_b64 s[26:27], s[28:29], s[26:27]
	v_cmp_gt_i32_e64 s[22:23], 48, v151
	s_and_b64 s[24:25], s[26:27], s[24:25]
	v_cmp_gt_i32_e64 s[20:21], 43, v151
	s_and_b64 s[22:23], s[24:25], s[22:23]
	v_cmp_gt_i32_e64 s[18:19], 42, v151
	s_and_b64 s[20:21], s[22:23], s[20:21]
	v_cmp_gt_i32_e64 s[16:17], 41, v151
	s_and_b64 s[18:19], s[20:21], s[18:19]
	v_cmp_gt_i32_e64 s[14:15], 40, v151
	s_and_b64 s[16:17], s[18:19], s[16:17]
	v_cmp_gt_i32_e64 s[12:13], 35, v151
	s_and_b64 s[14:15], s[16:17], s[14:15]
	v_cmp_gt_i32_e64 s[10:11], 34, v151
	s_and_b64 s[12:13], s[14:15], s[12:13]
	v_cmp_gt_i32_e64 s[8:9], 33, v151
	s_and_b64 s[10:11], s[12:13], s[10:11]
	v_cmp_gt_i32_e32 vcc, 32, v151
	s_and_b64 s[8:9], s[10:11], s[8:9]
	s_and_b64 vcc, s[8:9], vcc
	v_cndmask_b32_e64 v65, v49, v210, s[70:71]
	v_cndmask_b32_e64 v64, v48, v210, s[68:69]
	v_cndmask_b32_e64 v63, v47, v210, s[66:67]
	v_cndmask_b32_e64 v62, v46, v210, s[64:65]
	v_cndmask_b32_e64 v61, v45, v210, s[62:63]
	v_cndmask_b32_e64 v60, v44, v210, s[60:61]
	v_cndmask_b32_e64 v59, v43, v210, s[58:59]
	v_cndmask_b32_e64 v58, v42, v210, s[56:57]
	v_cndmask_b32_e64 v57, v41, v210, s[54:55]
	v_cndmask_b32_e64 v56, v40, v210, s[52:53]
	v_cndmask_b32_e64 v55, v39, v210, s[50:51]
	v_cndmask_b32_e64 v54, v38, v210, s[48:49]
	v_cndmask_b32_e64 v53, v37, v210, s[46:47]
	v_cndmask_b32_e64 v52, v36, v210, s[44:45]
	v_cndmask_b32_e64 v51, v35, v210, s[42:43]
	v_cndmask_b32_e64 v81, v33, v210, s[40:41]
	v_cndmask_b32_e64 v80, v32, v210, s[36:37]
	v_cndmask_b32_e64 v79, v31, v210, s[34:35]
	v_cndmask_b32_e64 v78, v30, v210, s[30:31]
	v_cndmask_b32_e64 v77, v29, v210, s[28:29]
	v_cndmask_b32_e64 v76, v28, v210, s[26:27]
	v_cndmask_b32_e64 v75, v27, v210, s[24:25]
	v_cndmask_b32_e64 v74, v26, v210, s[22:23]
	v_cndmask_b32_e64 v73, v25, v210, s[20:21]
	v_cndmask_b32_e64 v72, v24, v210, s[18:19]
	v_cndmask_b32_e64 v71, v23, v210, s[16:17]
	v_cndmask_b32_e64 v70, v22, v210, s[14:15]
	v_cndmask_b32_e64 v69, v21, v210, s[12:13]
	v_cndmask_b32_e64 v68, v20, v210, s[10:11]
	v_cndmask_b32_e64 v67, v19, v210, s[8:9]
	v_cndmask_b32_e32 v66, v18, v210, vcc
	s_branch .LBB0_332
